# v32 plus: cb64 cross-half row-max exchange via v_permlane32_swap instead of ds_bpermute
# baseline (speedup 1.0000x reference)
; __device__ __forceinline__ void cb_soft(const f32x16& s, int s0, int qpos, float bfar, const LAS float* bias_h, int lane, f32x16& o0, f32x16& o1, float& mrun, float& lrun, bf16x8 (&pf)[2]) {
;     ...
;     float mx = p[0];
; #pragma unroll
;     for (int r = 1; r < 16; ++r) mx = __builtin_fmaxf(mx, p[r]);
;     mx = __builtin_fmaxf(mx, __shfl_xor(mx, 32));
;     if (__any(mx > mrun)) {
;         const float mn = __builtin_fmaxf(mrun, mx), al = __builtin_amdgcn_exp2f(mrun - mn); mrun = mn; lrun *= al;
; #pragma unroll
;         for (int r = 0; r < 16; ++r) { o0[r] *= al; o1[r] *= al; }
; __device__ __forceinline__ void attn_unit_cb64(const AttnCtx& C, int b, int h, int c, LAS unsigned char* vlds, const LAS float* bias_h, int lane) {
;     ...
;         cb_soft(sA, s0, qposA, bfar, bias_h, lane, oA0, oA1, mA, lA, pfA);
.LBB0_399:
	s_nop 0
	v_max_f32_e32 v2, v81, v81
	v_max_f32_e32 v3, v80, v80
	v_max_f32_e32 v2, v3, v2
	v_max3_f32 v2, v2, v82, v83
	v_max3_f32 v2, v2, v84, v85
	v_max3_f32 v2, v2, v86, v87
	v_and_b32_e32 v4, 64, v244
	v_max3_f32 v2, v2, v88, v89
	v_xor_b32_e32 v3, 32, v244
	v_add_u32_e32 v4, 64, v4
	v_max3_f32 v2, v2, v90, v91
	v_cmp_lt_i32_e32 vcc, v3, v4
	v_max3_f32 v2, v2, v92, v93
	v_max3_f32 v2, v2, v94, v95
	v_cndmask_b32_e32 v3, v244, v3, vcc
	v_lshlrev_b32_e32 v14, 2, v3
	v_mov_b32_e32 v3, v2
	s_nop 1
	v_permlane32_swap_b32_e32 v3, v2
	v_max_f32_e32 v2, v2, v3
	v_cmp_gt_f32_e32 vcc, v2, v232
	s_cbranch_vccz .LBB0_401
	v_max_f32_e32 v2, v2, v2
	v_max_f32_e32 v3, v232, v232
	v_max_f32_e32 v3, v3, v2
	v_sub_f32_e32 v2, v232, v3
	v_exp_f32_e32 v2, v2
	v_mov_b32_e32 v232, v3
	v_mul_f32_e32 v229, v229, v2
	v_pk_mul_f32 v[78:79], v[78:79], v[2:3] op_sel_hi:[1,0]
	v_pk_mul_f32 v[76:77], v[76:77], v[2:3] op_sel_hi:[1,0]
	v_pk_mul_f32 v[74:75], v[74:75], v[2:3] op_sel_hi:[1,0]
	v_pk_mul_f32 v[72:73], v[72:73], v[2:3] op_sel_hi:[1,0]
	v_pk_mul_f32 v[70:71], v[70:71], v[2:3] op_sel_hi:[1,0]
	v_pk_mul_f32 v[68:69], v[68:69], v[2:3] op_sel_hi:[1,0]
	v_pk_mul_f32 v[66:67], v[66:67], v[2:3] op_sel_hi:[1,0]
	v_pk_mul_f32 v[64:65], v[64:65], v[2:3] op_sel_hi:[1,0]
	v_pk_mul_f32 v[62:63], v[62:63], v[2:3] op_sel_hi:[1,0]
	v_pk_mul_f32 v[60:61], v[60:61], v[2:3] op_sel_hi:[1,0]
	v_pk_mul_f32 v[58:59], v[58:59], v[2:3] op_sel_hi:[1,0]
	v_pk_mul_f32 v[56:57], v[56:57], v[2:3] op_sel_hi:[1,0]
	v_pk_mul_f32 v[54:55], v[54:55], v[2:3] op_sel_hi:[1,0]
	v_pk_mul_f32 v[52:53], v[52:53], v[2:3] op_sel_hi:[1,0]
	v_pk_mul_f32 v[50:51], v[50:51], v[2:3] op_sel_hi:[1,0]
	v_pk_mul_f32 v[48:49], v[48:49], v[2:3] op_sel_hi:[1,0]

; __device__ __forceinline__ void cb_soft(const f32x16& s, int s0, int qpos, float bfar, const LAS float* bias_h, int lane, f32x16& o0, f32x16& o1, float& mrun, float& lrun, bf16x8 (&pf)[2]) {
;     ...
;     float mx = p[0];
; #pragma unroll
;     for (int r = 1; r < 16; ++r) mx = __builtin_fmaxf(mx, p[r]);
;     mx = __builtin_fmaxf(mx, __shfl_xor(mx, 32));
;     if (__any(mx > mrun)) {
;         const float mn = __builtin_fmaxf(mrun, mx), al = __builtin_amdgcn_exp2f(mrun - mn); mrun = mn; lrun *= al;
; #pragma unroll
;         for (int r = 0; r < 16; ++r) { o0[r] *= al; o1[r] *= al; }
; __device__ __forceinline__ void attn_unit_cb64(const AttnCtx& C, int b, int h, int c, LAS unsigned char* vlds, const LAS float* bias_h, int lane) {
;     ...
;         cb_soft(sB, s0, qposA + 32, bfar, bias_h, lane, oB0, oB1, mB, lB, pfB);
.LBB0_405:
	s_nop 0
	v_max_f32_e32 v0, v113, v113
	v_max_f32_e32 v2, v112, v112
	v_max_f32_e32 v0, v2, v0
	v_max3_f32 v0, v0, v114, v115
	v_max3_f32 v0, v0, v116, v117
	v_max3_f32 v0, v0, v118, v119
	v_max3_f32 v0, v0, v120, v121
	v_max3_f32 v0, v0, v122, v123
	v_max3_f32 v0, v0, v124, v125
	v_max3_f32 v0, v0, v126, v127
	v_mov_b32_e32 v2, v0
	s_nop 1
	v_permlane32_swap_b32_e32 v2, v0
	v_max_f32_e32 v0, v0, v2
	v_cmp_gt_f32_e32 vcc, v0, v231
	s_cbranch_vccz .LBB0_392
	v_max_f32_e32 v0, v0, v0
	v_max_f32_e32 v2, v231, v231
	v_max_f32_e32 v2, v2, v0
	v_sub_f32_e32 v0, v231, v2
	v_exp_f32_e32 v0, v0
	v_mov_b32_e32 v231, v2
	v_mul_f32_e32 v228, v228, v0
	v_pk_mul_f32 v[46:47], v[46:47], v[0:1] op_sel_hi:[1,0]
	v_pk_mul_f32 v[44:45], v[44:45], v[0:1] op_sel_hi:[1,0]
	v_pk_mul_f32 v[42:43], v[42:43], v[0:1] op_sel_hi:[1,0]
	v_pk_mul_f32 v[40:41], v[40:41], v[0:1] op_sel_hi:[1,0]
	v_pk_mul_f32 v[38:39], v[38:39], v[0:1] op_sel_hi:[1,0]
	v_pk_mul_f32 v[36:37], v[36:37], v[0:1] op_sel_hi:[1,0]
	v_pk_mul_f32 v[34:35], v[34:35], v[0:1] op_sel_hi:[1,0]
	v_pk_mul_f32 v[32:33], v[32:33], v[0:1] op_sel_hi:[1,0]
	v_pk_mul_f32 v[30:31], v[30:31], v[0:1] op_sel_hi:[1,0]
	v_pk_mul_f32 v[28:29], v[28:29], v[0:1] op_sel_hi:[1,0]
	v_pk_mul_f32 v[26:27], v[26:27], v[0:1] op_sel_hi:[1,0]
	v_pk_mul_f32 v[24:25], v[24:25], v[0:1] op_sel_hi:[1,0]
	v_pk_mul_f32 v[22:23], v[22:23], v[0:1] op_sel_hi:[1,0]
	v_pk_mul_f32 v[20:21], v[20:21], v[0:1] op_sel_hi:[1,0]
	v_pk_mul_f32 v[18:19], v[18:19], v[0:1] op_sel_hi:[1,0]
	v_pk_mul_f32 v[16:17], v[16:17], v[0:1] op_sel_hi:[1,0]
	s_branch .LBB0_392
